# barrier 6 (P5->P6): leader skips the L2 write-back (P5 outputs are consumed on the same XCD; barrier 8 writes back), rendezvous kept
# speedup vs baseline: 1.0078x; 1.0024x over previous
; __device__ __forceinline__ unsigned xb_add(unsigned* p, unsigned v) { return __hip_atomic_fetch_add(p, v, __ATOMIC_RELAXED, __HIP_MEMORY_SCOPE_AGENT); }
; __device__ __forceinline__ void xcd_barrier(const XcdBarrier& b) {
;     ...
;             __builtin_amdgcn_fence(__ATOMIC_RELEASE, "agent");
;             asm volatile("s_waitcnt vmcnt(0)" ::: "memory");
;             const unsigned og = xb_add(&bar[XB_TOP], 1u);
;             const unsigned tg = og / nx;
;             if (og + 1u == (tg + 1u) * nx) xb_add(&bar[XB_TOPGEN], 1u);
.Lxl6_nowb:
	s_waitcnt lgkmcnt(0)
	s_waitcnt vmcnt(0)
	v_mbcnt_lo_u32_b32 v1, s12, 0
	v_mbcnt_hi_u32_b32 v1, s13, v1
	v_cmp_eq_u32_e32 vcc, 0, v1
	s_and_saveexec_b64 s[14:15], vcc
	s_cbranch_execz .LBB0_951
	s_bcnt1_i32_b64 s3, s[12:13]
	v_mov_b32_e32 v2, 0x83000
	v_mov_b32_e32 v3, s3
	global_atomic_add v2, v2, v3, s[68:69] offset:1024 sc0
